# speedup vs baseline: 1.0062x; 1.0036x over previous
; #define PG8_WAIT_V(n) asm volatile("s_waitcnt vmcnt(" #n ")" ::: "memory")
; #define PG8_BAR __builtin_amdgcn_s_barrier()
; template <class Epi, class Pre, bool AG = false>
; __device__ __forceinline__ void gemm_phase(LAS unsigned char* lds, const Gemm g, const StaticOrder& S, const Epi& E, const Pre& P) {
;     ...
;     P(S);
;     if (wr == 1) PG8_BAR;
;     PG8_WAIT_V(2); PG8_BAR;
; template <int NS> __device__ __forceinline__ void prep_rstd(LAS unsigned char* lds, const float* part, const pg8::StaticOrder& S, float inv_n) {
;     ...
;     __syncthreads();
.LBB0_204:
	s_ashr_i32 s6, s16, 8
	s_cmp_eq_u32 s6, 1
	s_cselect_b64 s[0:1], -1, 0
	s_cmp_lg_u32 s6, 1
	s_waitcnt vmcnt(0) lgkmcnt(0)
	s_barrier
	s_cbranch_scc1 .LBB0_206
	s_setprio 1
	s_barrier

; #define PG8_STAGE(bufoff, gbase, voff) do { _Pragma("unroll") for (int _i = 0; _i < 2; ++_i) \
;         __builtin_amdgcn_global_load_lds((const unsigned*)((const char*)(gbase) + (voff)[_i]), (LAS unsigned*)(lds + (bufoff) + ldsw + _i * 8192), 16, 0, 0); } while (0)
; #define PG8_LDA(dst, b, h) do { _Pragma("unroll") for (int m = 0; m < 4; ++m) _Pragma("unroll") for (int k = 0; k < 2; ++k) dst[m][k] = *(const LAS bf16x8*)(lds + PG8_SA(b, h) + aoff + m * 2048 + k * 1024); } while (0)
; #define PG8_LDB(dst, b, h) do { _Pragma("unroll") for (int n = 0; n < 2; ++n) _Pragma("unroll") for (int k = 0; k < 2; ++k) dst[n][k] = *(const LAS bf16x8*)(lds + PG8_SB(b, h) + boff + n * 2048 + k * 1024); } while (0)
; #define PG8_MMA(ai, bj, At, Bt) do { __builtin_amdgcn_s_setprio(1); _Pragma("unroll") for (int m = 0; m < 4; ++m) _Pragma("unroll") for (int n = 0; n < 2; ++n) _Pragma("unroll") for (int k = 0; k < 2; ++k) \
;         acc[ai][bj][m][n] = __builtin_amdgcn_mfma_f32_16x16x32_bf16(Bt[n][k], At[m][k], acc[ai][bj][m][n], 0, 0, 0); __builtin_amdgcn_s_setprio(0); } while (0)
; #define PG8_WAIT_V(n) asm volatile("s_waitcnt vmcnt(" #n ")" ::: "memory")
; #define PG8_WAIT_L(n) asm volatile("s_waitcnt lgkmcnt(" #n ")" ::: "memory")
; #define PG8_BAR __builtin_amdgcn_s_barrier()
; #define PG8_SCHED __builtin_amdgcn_sched_barrier(0)
; template <class Epi, class Pre, bool AG = false>
; __device__ __forceinline__ void gemm_phase(LAS unsigned char* lds, const Gemm g, const StaticOrder& S, const Epi& E, const Pre& P) {
;     ...
;             PG8_LDB(B0, 0, 0); PG8_LDB(B1, 0, 1); PG8_SCHED; PG8_LDA(At, 0, 0); PG8_STAGE(PG8_SA(1, 1), a1 + hstepA, voffA);
;             PG8_WAIT_V(8); PG8_WAIT_L(0); PG8_BAR; PG8_MMA(0, 0, At, B0); PG8_MMA(0, 1, At, B1); PG8_BAR; PG8_SCHED;
;             PG8_LDA(At, 0, 1); PG8_STAGE(PG8_SB(0, 0), b2, voffB); PG8_STAGE(PG8_SB(0, 1), b2 + hstep, voffB); PG8_STAGE(PG8_SA(0, 0), a2, voffA);
.Lpw_gu_0_done:
	s_waitcnt lgkmcnt(0)
	s_barrier
	v_mfma_f32_16x16x32_bf16 v[122:125], v[140:143], v[174:177], 0
	v_mfma_f32_16x16x32_bf16 v[114:117], v[150:153], v[174:177], 0
	v_mfma_f32_16x16x32_bf16 v[106:109], v[140:143], v[198:201], 0
	v_mfma_f32_16x16x32_bf16 v[98:101], v[150:153], v[198:201], 0
	v_mfma_f32_16x16x32_bf16 v[90:93], v[140:143], v[206:209], 0
	v_mfma_f32_16x16x32_bf16 v[82:85], v[150:153], v[206:209], 0
	v_mfma_f32_16x16x32_bf16 v[74:77], v[140:143], v[214:217], 0
	v_mfma_f32_16x16x32_bf16 v[66:69], v[150:153], v[214:217], 0
	v_mfma_f32_16x16x32_bf16 v[122:125], v[144:147], v[194:197], v[122:125]
	v_mfma_f32_16x16x32_bf16 v[114:117], v[154:157], v[194:197], v[114:117]
	v_mfma_f32_16x16x32_bf16 v[106:109], v[144:147], v[202:205], v[106:109]
	v_mfma_f32_16x16x32_bf16 v[98:101], v[154:157], v[202:205], v[98:101]
	v_mfma_f32_16x16x32_bf16 v[90:93], v[144:147], v[210:213], v[90:93]
	v_mfma_f32_16x16x32_bf16 v[82:85], v[154:157], v[210:213], v[82:85]
	v_mfma_f32_16x16x32_bf16 v[74:77], v[144:147], v[218:221], v[74:77]
	v_mfma_f32_16x16x32_bf16 v[66:69], v[154:157], v[218:221], v[66:69]
	v_mfma_f32_16x16x32_bf16 v[126:129], v[158:161], v[174:177], 0
	v_mfma_f32_16x16x32_bf16 v[118:121], v[166:169], v[174:177], 0
	v_mfma_f32_16x16x32_bf16 v[110:113], v[158:161], v[198:201], 0
	v_mfma_f32_16x16x32_bf16 v[102:105], v[166:169], v[198:201], 0
	v_mfma_f32_16x16x32_bf16 v[94:97], v[158:161], v[206:209], 0
	v_mfma_f32_16x16x32_bf16 v[86:89], v[166:169], v[206:209], 0
	v_mfma_f32_16x16x32_bf16 v[78:81], v[158:161], v[214:217], 0
	v_mfma_f32_16x16x32_bf16 v[70:73], v[166:169], v[214:217], 0
	v_mfma_f32_16x16x32_bf16 v[126:129], v[162:165], v[194:197], v[126:129]
	v_mfma_f32_16x16x32_bf16 v[118:121], v[170:173], v[194:197], v[118:121]
	v_mfma_f32_16x16x32_bf16 v[110:113], v[162:165], v[202:205], v[110:113]
	v_mfma_f32_16x16x32_bf16 v[102:105], v[170:173], v[202:205], v[102:105]
	v_mfma_f32_16x16x32_bf16 v[94:97], v[162:165], v[210:213], v[94:97]
	v_mfma_f32_16x16x32_bf16 v[86:89], v[170:173], v[210:213], v[86:89]
	v_mfma_f32_16x16x32_bf16 v[78:81], v[162:165], v[218:221], v[78:81]
	v_mfma_f32_16x16x32_bf16 v[70:73], v[170:173], v[218:221], v[70:73]
	s_barrier
	s_add_i32 s84, s84, s31
	v_lshl_add_u64 v[178:179], s[46:47], 0, v[134:135]
	s_mov_b32 m0, s84
	ds_read_b128 v[174:177], v149 offset:16384
	ds_read_b128 v[194:197], v149 offset:17408
	ds_read_b128 v[198:201], v149 offset:18432
	ds_read_b128 v[202:205], v149 offset:19456
	ds_read_b128 v[206:209], v149 offset:20480
	ds_read_b128 v[210:213], v149 offset:21504
	ds_read_b128 v[214:217], v149 offset:22528
	ds_read_b128 v[218:221], v149 offset:23552
	global_load_lds_dwordx4 v[178:179], off
	s_add_i32 m0, s84, 0x2000
	s_add_u32 s84, s46, 0x40000
	v_lshl_add_u64 v[180:181], s[46:47], 0, v[130:131]
	s_addc_u32 s85, s47, 0
	s_add_i32 s86, s86, s31
	global_load_lds_dwordx4 v[180:181], off
	v_lshl_add_u64 v[182:183], s[84:85], 0, v[134:135]
	s_mov_b32 m0, s86
	v_lshl_add_u64 v[188:189], s[54:55], 0, v[132:133]
	global_load_lds_dwordx4 v[182:183], off
	v_lshl_add_u64 v[182:183], s[84:85], 0, v[130:131]
	s_add_i32 m0, s86, 0x2000
	s_nop 0
	global_load_lds_dwordx4 v[182:183], off
	v_lshl_add_u64 v[182:183], s[54:55], 0, v[136:137]
	s_mov_b32 m0, s38
	s_nop 0
	global_load_lds_dwordx4 v[182:183], off
	s_mov_b32 m0, s48
	s_nop 0
	global_load_lds_dwordx4 v[188:189], off
	s_cmp_eq_u32 s70, 0
	s_cbranch_scc1 .Lpw_gu_1
	s_waitcnt vmcnt(16)
	s_branch .Lpw_gu_1_done

; #define PG8_STAGE(bufoff, gbase, voff) do { _Pragma("unroll") for (int _i = 0; _i < 2; ++_i) \
;         __builtin_amdgcn_global_load_lds((const unsigned*)((const char*)(gbase) + (voff)[_i]), (LAS unsigned*)(lds + (bufoff) + ldsw + _i * 8192), 16, 0, 0); } while (0)
; #define PG8_LDA(dst, b, h) do { _Pragma("unroll") for (int m = 0; m < 4; ++m) _Pragma("unroll") for (int k = 0; k < 2; ++k) dst[m][k] = *(const LAS bf16x8*)(lds + PG8_SA(b, h) + aoff + m * 2048 + k * 1024); } while (0)
; #define PG8_LDB(dst, b, h) do { _Pragma("unroll") for (int n = 0; n < 2; ++n) _Pragma("unroll") for (int k = 0; k < 2; ++k) dst[n][k] = *(const LAS bf16x8*)(lds + PG8_SB(b, h) + boff + n * 2048 + k * 1024); } while (0)
; #define PG8_MMA(ai, bj, At, Bt) do { __builtin_amdgcn_s_setprio(1); _Pragma("unroll") for (int m = 0; m < 4; ++m) _Pragma("unroll") for (int n = 0; n < 2; ++n) _Pragma("unroll") for (int k = 0; k < 2; ++k) \
;         acc[ai][bj][m][n] = __builtin_amdgcn_mfma_f32_16x16x32_bf16(Bt[n][k], At[m][k], acc[ai][bj][m][n], 0, 0, 0); __builtin_amdgcn_s_setprio(0); } while (0)
; #define PG8_WAIT_V(n) asm volatile("s_waitcnt vmcnt(" #n ")" ::: "memory")
; #define PG8_WAIT_L(n) asm volatile("s_waitcnt lgkmcnt(" #n ")" ::: "memory")
; #define PG8_BAR __builtin_amdgcn_s_barrier()
; #define PG8_SCHED __builtin_amdgcn_sched_barrier(0)
; template <class Epi, class Pre, bool AG = false>
; __device__ __forceinline__ void gemm_phase(LAS unsigned char* lds, const Gemm g, const StaticOrder& S, const Epi& E, const Pre& P) {
;     ...
;             PG8_LDA(At, 0, 1); PG8_STAGE(PG8_SB(0, 0), b2, voffB); PG8_STAGE(PG8_SB(0, 1), b2 + hstep, voffB); PG8_STAGE(PG8_SA(0, 0), a2, voffA);
;             PG8_WAIT_V(8); PG8_WAIT_L(0); PG8_BAR; PG8_MMA(1, 0, At, B0); PG8_MMA(1, 1, At, B1); PG8_BAR; PG8_SCHED;
;             PG8_LDB(B0, 1, 0); PG8_LDB(B1, 1, 1); PG8_SCHED; PG8_LDA(At, 1, 0); PG8_STAGE(PG8_SA(0, 1), a2 + hstepA, voffA);
;             PG8_WAIT_V(8); PG8_WAIT_L(0); PG8_BAR; PG8_MMA(0, 0, At, B0); PG8_MMA(0, 1, At, B1); PG8_BAR; PG8_SCHED;
.Lpw_gu_1_done:
	s_waitcnt lgkmcnt(0)
	s_barrier
	v_mfma_f32_16x16x32_bf16 v[58:61], v[140:143], v[174:177], 0
	v_mfma_f32_16x16x32_bf16 v[50:53], v[150:153], v[174:177], 0
	v_mfma_f32_16x16x32_bf16 v[42:45], v[140:143], v[198:201], 0
	v_mfma_f32_16x16x32_bf16 v[34:37], v[150:153], v[198:201], 0
	v_mfma_f32_16x16x32_bf16 v[26:29], v[140:143], v[206:209], 0
	v_mfma_f32_16x16x32_bf16 v[18:21], v[150:153], v[206:209], 0
	v_mfma_f32_16x16x32_bf16 v[10:13], v[140:143], v[214:217], 0
	v_mfma_f32_16x16x32_bf16 v[6:9], v[150:153], v[214:217], 0
	v_mfma_f32_16x16x32_bf16 v[58:61], v[144:147], v[194:197], v[58:61]
	v_mfma_f32_16x16x32_bf16 v[50:53], v[154:157], v[194:197], v[50:53]
	v_mfma_f32_16x16x32_bf16 v[42:45], v[144:147], v[202:205], v[42:45]
	v_mfma_f32_16x16x32_bf16 v[34:37], v[154:157], v[202:205], v[34:37]
	v_mfma_f32_16x16x32_bf16 v[26:29], v[144:147], v[210:213], v[26:29]
	v_mfma_f32_16x16x32_bf16 v[18:21], v[154:157], v[210:213], v[18:21]
	v_mfma_f32_16x16x32_bf16 v[10:13], v[144:147], v[218:221], v[10:13]
	v_mfma_f32_16x16x32_bf16 v[6:9], v[154:157], v[218:221], v[6:9]
	v_mfma_f32_16x16x32_bf16 v[62:65], v[158:161], v[174:177], 0
	v_mfma_f32_16x16x32_bf16 v[54:57], v[166:169], v[174:177], 0
	v_mfma_f32_16x16x32_bf16 v[46:49], v[158:161], v[198:201], 0
	v_mfma_f32_16x16x32_bf16 v[38:41], v[166:169], v[198:201], 0
	v_mfma_f32_16x16x32_bf16 v[30:33], v[158:161], v[206:209], 0
	v_mfma_f32_16x16x32_bf16 v[22:25], v[166:169], v[206:209], 0
	v_mfma_f32_16x16x32_bf16 v[14:17], v[158:161], v[214:217], 0
	v_mfma_f32_16x16x32_bf16 v[2:5], v[166:169], v[214:217], 0
	v_mfma_f32_16x16x32_bf16 v[62:65], v[162:165], v[194:197], v[62:65]
	v_mfma_f32_16x16x32_bf16 v[54:57], v[170:173], v[194:197], v[54:57]
	v_mfma_f32_16x16x32_bf16 v[46:49], v[162:165], v[202:205], v[46:49]
	v_mfma_f32_16x16x32_bf16 v[38:41], v[170:173], v[202:205], v[38:41]
	v_mfma_f32_16x16x32_bf16 v[30:33], v[162:165], v[210:213], v[30:33]
	v_mfma_f32_16x16x32_bf16 v[22:25], v[170:173], v[210:213], v[22:25]
	v_mfma_f32_16x16x32_bf16 v[14:17], v[162:165], v[218:221], v[14:17]
	v_mfma_f32_16x16x32_bf16 v[2:5], v[170:173], v[218:221], v[2:5]
	s_barrier
	s_add_i32 s84, 0, 0x18000
	s_add_i32 s85, 0, 0x1c000
	v_add_u32_e32 v154, s84, v148
	v_add_u32_e32 v170, s85, v148
	ds_read_b128 v[140:143], v154
	ds_read_b128 v[144:147], v154 offset:1024
	ds_read_b128 v[150:153], v154 offset:2048
	ds_read_b128 v[154:157], v154 offset:3072
	ds_read_b128 v[158:161], v170
	ds_read_b128 v[162:165], v170 offset:1024
	ds_read_b128 v[166:169], v170 offset:2048
	ds_read_b128 v[170:173], v170 offset:3072
	s_add_u32 s54, s54, 0x40000
	s_addc_u32 s55, s55, 0
	s_mov_b32 m0, s49
	v_lshl_add_u64 v[190:191], s[54:55], 0, v[136:137]
	ds_read_b128 v[174:177], v149 offset:32768
	ds_read_b128 v[194:197], v149 offset:33792
	ds_read_b128 v[198:201], v149 offset:34816
	ds_read_b128 v[202:205], v149 offset:35840
	ds_read_b128 v[206:209], v149 offset:36864
	ds_read_b128 v[210:213], v149 offset:37888
	ds_read_b128 v[214:217], v149 offset:38912
	ds_read_b128 v[218:221], v149 offset:39936
	global_load_lds_dwordx4 v[190:191], off
	v_lshl_add_u64 v[190:191], s[54:55], 0, v[132:133]
	s_mov_b32 m0, s53
	s_nop 0
	global_load_lds_dwordx4 v[190:191], off
	s_waitcnt vmcnt(8)
	s_waitcnt lgkmcnt(0)
	s_barrier
	v_mfma_f32_16x16x32_bf16 v[122:125], v[140:143], v[174:177], v[122:125]
	v_mfma_f32_16x16x32_bf16 v[114:117], v[150:153], v[174:177], v[114:117]
	v_mfma_f32_16x16x32_bf16 v[106:109], v[140:143], v[198:201], v[106:109]
	v_mfma_f32_16x16x32_bf16 v[98:101], v[150:153], v[198:201], v[98:101]
	v_mfma_f32_16x16x32_bf16 v[90:93], v[140:143], v[206:209], v[90:93]
	v_mfma_f32_16x16x32_bf16 v[82:85], v[150:153], v[206:209], v[82:85]
	v_mfma_f32_16x16x32_bf16 v[74:77], v[140:143], v[214:217], v[74:77]
	v_mfma_f32_16x16x32_bf16 v[66:69], v[150:153], v[214:217], v[66:69]
	v_mfma_f32_16x16x32_bf16 v[122:125], v[144:147], v[194:197], v[122:125]
	v_mfma_f32_16x16x32_bf16 v[114:117], v[154:157], v[194:197], v[114:117]
	v_mfma_f32_16x16x32_bf16 v[106:109], v[144:147], v[202:205], v[106:109]
	v_mfma_f32_16x16x32_bf16 v[98:101], v[154:157], v[202:205], v[98:101]
	v_mfma_f32_16x16x32_bf16 v[90:93], v[144:147], v[210:213], v[90:93]
	v_mfma_f32_16x16x32_bf16 v[82:85], v[154:157], v[210:213], v[82:85]
	v_mfma_f32_16x16x32_bf16 v[74:77], v[144:147], v[218:221], v[74:77]
	v_mfma_f32_16x16x32_bf16 v[66:69], v[154:157], v[218:221], v[66:69]
	v_mfma_f32_16x16x32_bf16 v[126:129], v[158:161], v[174:177], v[126:129]
	v_mfma_f32_16x16x32_bf16 v[118:121], v[166:169], v[174:177], v[118:121]
	v_mfma_f32_16x16x32_bf16 v[110:113], v[158:161], v[198:201], v[110:113]
	v_mfma_f32_16x16x32_bf16 v[102:105], v[166:169], v[198:201], v[102:105]
	v_mfma_f32_16x16x32_bf16 v[94:97], v[158:161], v[206:209], v[94:97]
	v_mfma_f32_16x16x32_bf16 v[86:89], v[166:169], v[206:209], v[86:89]
	v_mfma_f32_16x16x32_bf16 v[78:81], v[158:161], v[214:217], v[78:81]
	v_mfma_f32_16x16x32_bf16 v[70:73], v[166:169], v[214:217], v[70:73]
	v_mfma_f32_16x16x32_bf16 v[126:129], v[162:165], v[194:197], v[126:129]
	v_mfma_f32_16x16x32_bf16 v[118:121], v[170:173], v[194:197], v[118:121]
	v_mfma_f32_16x16x32_bf16 v[110:113], v[162:165], v[202:205], v[110:113]
	v_mfma_f32_16x16x32_bf16 v[102:105], v[170:173], v[202:205], v[102:105]
	v_mfma_f32_16x16x32_bf16 v[94:97], v[162:165], v[210:213], v[94:97]
	v_mfma_f32_16x16x32_bf16 v[86:89], v[170:173], v[210:213], v[86:89]
	v_mfma_f32_16x16x32_bf16 v[78:81], v[162:165], v[218:221], v[78:81]
	v_mfma_f32_16x16x32_bf16 v[70:73], v[170:173], v[218:221], v[70:73]
	s_barrier
; #define PG8_STAGE(bufoff, gbase, voff) do { _Pragma("unroll") for (int _i = 0; _i < 2; ++_i) \
;         __builtin_amdgcn_global_load_lds((const unsigned*)((const char*)(gbase) + (voff)[_i]), (LAS unsigned*)(lds + (bufoff) + ldsw + _i * 8192), 16, 0, 0); } while (0)
; #define PG8_LDA(dst, b, h) do { _Pragma("unroll") for (int m = 0; m < 4; ++m) _Pragma("unroll") for (int k = 0; k < 2; ++k) dst[m][k] = *(const LAS bf16x8*)(lds + PG8_SA(b, h) + aoff + m * 2048 + k * 1024); } while (0)
; #define PG8_LDB(dst, b, h) do { _Pragma("unroll") for (int n = 0; n < 2; ++n) _Pragma("unroll") for (int k = 0; k < 2; ++k) dst[n][k] = *(const LAS bf16x8*)(lds + PG8_SB(b, h) + boff + n * 2048 + k * 1024); } while (0)
; #define PG8_MMA(ai, bj, At, Bt) do { __builtin_amdgcn_s_setprio(1); _Pragma("unroll") for (int m = 0; m < 4; ++m) _Pragma("unroll") for (int n = 0; n < 2; ++n) _Pragma("unroll") for (int k = 0; k < 2; ++k) \
;         acc[ai][bj][m][n] = __builtin_amdgcn_mfma_f32_16x16x32_bf16(Bt[n][k], At[m][k], acc[ai][bj][m][n], 0, 0, 0); __builtin_amdgcn_s_setprio(0); } while (0)
; #define PG8_WAIT_V(n) asm volatile("s_waitcnt vmcnt(" #n ")" ::: "memory")
; template <class Epi, class Pre, bool AG = false>
; __device__ __forceinline__ void gemm_phase(LAS unsigned char* lds, const Gemm g, const StaticOrder& S, const Epi& E, const Pre& P) {
;     ...
;             PG8_LDB(B0, 0, 0); PG8_LDB(B1, 0, 1); PG8_SCHED; PG8_LDA(At, 0, 0); PG8_STAGE(PG8_SA(1, 1), a1 + hstepA, voffA);
;             PG8_WAIT_V(8); PG8_WAIT_L(0); PG8_BAR; PG8_MMA(0, 0, At, B0); PG8_MMA(0, 1, At, B1); PG8_BAR; PG8_SCHED;
;             PG8_LDA(At, 0, 1); PG8_STAGE(PG8_SB(0, 0), b2, voffB); PG8_STAGE(PG8_SB(0, 1), b2 + hstep, voffB); PG8_STAGE(PG8_SA(0, 0), a2, voffA);
;             PG8_WAIT_V(8); PG8_WAIT_L(0); PG8_BAR; PG8_MMA(1, 0, At, B0); PG8_MMA(1, 1, At, B1); PG8_BAR; PG8_SCHED;
;             PG8_LDB(B0, 1, 0); PG8_LDB(B1, 1, 1); PG8_SCHED; PG8_LDA(At, 1, 0); PG8_STAGE(PG8_SA(0, 1), a2 + hstepA, voffA);
;             PG8_WAIT_V(8); PG8_WAIT_L(0); PG8_BAR; PG8_MMA(0, 0, At, B0); PG8_MMA(0, 1, At, B1); PG8_BAR; PG8_SCHED;
;             PG8_LDA(At, 1, 1); PG8_STAGE(PG8_SB(1, 0), b3, voffB); PG8_STAGE(PG8_SB(1, 1), b3 + hstep, voffB); PG8_STAGE(PG8_SA(1, 0), a3, voffA);
;             PG8_WAIT_V(8); PG8_WAIT_L(0); PG8_BAR; PG8_MMA(1, 0, At, B0); PG8_MMA(1, 1, At, B1); PG8_BAR; PG8_SCHED;
	s_add_i32 s54, s84, s31
	v_lshl_add_u64 v[178:179], v[178:179], 0, s[66:67]
	s_mov_b32 m0, s54
	ds_read_b128 v[174:177], v149 offset:49152
	ds_read_b128 v[194:197], v149 offset:50176
	ds_read_b128 v[198:201], v149 offset:51200
	ds_read_b128 v[202:205], v149 offset:52224
	ds_read_b128 v[206:209], v149 offset:53248
	ds_read_b128 v[210:213], v149 offset:54272
	ds_read_b128 v[214:217], v149 offset:55296
	ds_read_b128 v[218:221], v149 offset:56320
	global_load_lds_dwordx4 v[178:179], off
	s_add_i32 m0, s54, 0x2000
	s_add_u32 s46, s46, 0x40080
	v_lshl_add_u64 v[178:179], v[180:181], 0, s[66:67]
	s_addc_u32 s47, s47, 0
	s_add_i32 s54, s85, s31
	global_load_lds_dwordx4 v[178:179], off
	v_lshl_add_u64 v[178:179], s[46:47], 0, v[134:135]
	s_mov_b32 m0, s54
	s_nop 0
	global_load_lds_dwordx4 v[178:179], off
	v_lshl_add_u64 v[178:179], s[46:47], 0, v[130:131]
	s_add_i32 m0, s54, 0x2000
	s_nop 0
	global_load_lds_dwordx4 v[178:179], off
	v_lshl_add_u64 v[178:179], v[182:183], 0, s[66:67]
	s_mov_b32 m0, s58
	s_nop 0
	global_load_lds_dwordx4 v[178:179], off
	v_lshl_add_u64 v[178:179], v[188:189], 0, s[66:67]
	s_mov_b32 m0, s59
	s_nop 0
	global_load_lds_dwordx4 v[178:179], off
	s_waitcnt vmcnt(8)
	s_waitcnt lgkmcnt(0)
	s_barrier
	v_mfma_f32_16x16x32_bf16 v[58:61], v[140:143], v[174:177], v[58:61]
	v_mfma_f32_16x16x32_bf16 v[50:53], v[150:153], v[174:177], v[50:53]
	v_mfma_f32_16x16x32_bf16 v[42:45], v[140:143], v[198:201], v[42:45]
	v_mfma_f32_16x16x32_bf16 v[34:37], v[150:153], v[198:201], v[34:37]
	v_mfma_f32_16x16x32_bf16 v[26:29], v[140:143], v[206:209], v[26:29]
	v_mfma_f32_16x16x32_bf16 v[18:21], v[150:153], v[206:209], v[18:21]
	v_mfma_f32_16x16x32_bf16 v[10:13], v[140:143], v[214:217], v[10:13]
	v_mfma_f32_16x16x32_bf16 v[6:9], v[150:153], v[214:217], v[6:9]
	v_mfma_f32_16x16x32_bf16 v[58:61], v[144:147], v[194:197], v[58:61]
	v_mfma_f32_16x16x32_bf16 v[50:53], v[154:157], v[194:197], v[50:53]
	v_mfma_f32_16x16x32_bf16 v[42:45], v[144:147], v[202:205], v[42:45]
	v_mfma_f32_16x16x32_bf16 v[34:37], v[154:157], v[202:205], v[34:37]
	v_mfma_f32_16x16x32_bf16 v[26:29], v[144:147], v[210:213], v[26:29]
	v_mfma_f32_16x16x32_bf16 v[18:21], v[154:157], v[210:213], v[18:21]
	v_mfma_f32_16x16x32_bf16 v[10:13], v[144:147], v[218:221], v[10:13]
	v_mfma_f32_16x16x32_bf16 v[6:9], v[154:157], v[218:221], v[6:9]
	v_mfma_f32_16x16x32_bf16 v[62:65], v[158:161], v[174:177], v[62:65]
	v_mfma_f32_16x16x32_bf16 v[54:57], v[166:169], v[174:177], v[54:57]
	v_mfma_f32_16x16x32_bf16 v[46:49], v[158:161], v[198:201], v[46:49]
	v_mfma_f32_16x16x32_bf16 v[38:41], v[166:169], v[198:201], v[38:41]
	v_mfma_f32_16x16x32_bf16 v[30:33], v[158:161], v[206:209], v[30:33]
	v_mfma_f32_16x16x32_bf16 v[22:25], v[166:169], v[206:209], v[22:25]
	v_mfma_f32_16x16x32_bf16 v[14:17], v[158:161], v[214:217], v[14:17]
	v_mfma_f32_16x16x32_bf16 v[2:5], v[166:169], v[214:217], v[2:5]
	v_mfma_f32_16x16x32_bf16 v[62:65], v[162:165], v[194:197], v[62:65]
	v_mfma_f32_16x16x32_bf16 v[54:57], v[170:173], v[194:197], v[54:57]
	v_mfma_f32_16x16x32_bf16 v[46:49], v[162:165], v[202:205], v[46:49]
	v_mfma_f32_16x16x32_bf16 v[38:41], v[170:173], v[202:205], v[38:41]
	v_mfma_f32_16x16x32_bf16 v[30:33], v[162:165], v[210:213], v[30:33]
	v_mfma_f32_16x16x32_bf16 v[22:25], v[170:173], v[210:213], v[22:25]
	v_mfma_f32_16x16x32_bf16 v[14:17], v[162:165], v[218:221], v[14:17]
	v_mfma_f32_16x16x32_bf16 v[2:5], v[170:173], v[218:221], v[2:5]
	s_barrier
	s_add_i32 s79, s79, 2
	s_add_u32 s44, s44, 0x100
	s_addc_u32 s45, s45, 0
	s_add_u32 s76, s76, 0x100
	s_addc_u32 s77, s77, 0
	s_cmp_gt_u32 s79, 13
	s_cbranch_scc0 .LBB0_212
	s_branch .Lpeel_gu_after
.LBB0_212:
	s_add_u32 s46, s44, 0xfffc0080
	s_addc_u32 s47, s45, -1
	s_add_i32 s84, 0, 0x10000
	s_cmp_eq_u32 s79, 12
	s_cselect_b32 s55, s12, s47
	s_cselect_b32 s54, s13, s46
	s_cselect_b32 s47, s17, s77
	s_cselect_b32 s46, s27, s76
	s_add_i32 s86, 0, 0x14000
	v_add_u32_e32 v154, s84, v148
	v_add_u32_e32 v170, s86, v148
	ds_read_b128 v[140:143], v154
	ds_read_b128 v[144:147], v154 offset:1024
	ds_read_b128 v[150:153], v154 offset:2048
	ds_read_b128 v[154:157], v154 offset:3072
	ds_read_b128 v[158:161], v170
	ds_read_b128 v[162:165], v170 offset:1024
	ds_read_b128 v[166:169], v170 offset:2048
	ds_read_b128 v[170:173], v170 offset:3072
	v_lshl_add_u64 v[178:179], s[44:45], 0, v[0:1]
	s_add_i32 m0, s38, 0xc000
	ds_read_b128 v[174:177], v149
	ds_read_b128 v[194:197], v149 offset:1024
	ds_read_b128 v[198:201], v149 offset:2048
	ds_read_b128 v[202:205], v149 offset:3072
	ds_read_b128 v[206:209], v149 offset:4096
	ds_read_b128 v[210:213], v149 offset:5120
	ds_read_b128 v[214:217], v149 offset:6144
	ds_read_b128 v[218:221], v149 offset:7168
	global_load_lds_dwordx4 v[178:179], off
	v_lshl_add_u64 v[178:179], s[44:45], 0, v[138:139]
	s_add_i32 m0, s38, 0xe000
	s_nop 0
	global_load_lds_dwordx4 v[178:179], off
	s_waitcnt vmcnt(8)
	s_waitcnt lgkmcnt(0)
	s_barrier
; #define PG8_STAGE(bufoff, gbase, voff) do { _Pragma("unroll") for (int _i = 0; _i < 2; ++_i) \
;         __builtin_amdgcn_global_load_lds((const unsigned*)((const char*)(gbase) + (voff)[_i]), (LAS unsigned*)(lds + (bufoff) + ldsw + _i * 8192), 16, 0, 0); } while (0)
; #define PG8_LDA(dst, b, h) do { _Pragma("unroll") for (int m = 0; m < 4; ++m) _Pragma("unroll") for (int k = 0; k < 2; ++k) dst[m][k] = *(const LAS bf16x8*)(lds + PG8_SA(b, h) + aoff + m * 2048 + k * 1024); } while (0)
; #define PG8_LDB(dst, b, h) do { _Pragma("unroll") for (int n = 0; n < 2; ++n) _Pragma("unroll") for (int k = 0; k < 2; ++k) dst[n][k] = *(const LAS bf16x8*)(lds + PG8_SB(b, h) + boff + n * 2048 + k * 1024); } while (0)
; #define PG8_MMA(ai, bj, At, Bt) do { __builtin_amdgcn_s_setprio(1); _Pragma("unroll") for (int m = 0; m < 4; ++m) _Pragma("unroll") for (int n = 0; n < 2; ++n) _Pragma("unroll") for (int k = 0; k < 2; ++k) \
;         acc[ai][bj][m][n] = __builtin_amdgcn_mfma_f32_16x16x32_bf16(Bt[n][k], At[m][k], acc[ai][bj][m][n], 0, 0, 0); __builtin_amdgcn_s_setprio(0); } while (0)
; #define PG8_WAIT_V(n) asm volatile("s_waitcnt vmcnt(" #n ")" ::: "memory")
; #define PG8_WAIT_L(n) asm volatile("s_waitcnt lgkmcnt(" #n ")" ::: "memory")
; #define PG8_BAR __builtin_amdgcn_s_barrier()
; #define PG8_SCHED __builtin_amdgcn_sched_barrier(0)
; template <class Epi, class Pre, bool AG = false>
; __device__ __forceinline__ void gemm_phase(LAS unsigned char* lds, const Gemm g, const StaticOrder& S, const Epi& E, const Pre& P) {
;     ...
;             PG8_LDB(B0, 0, 0); PG8_LDB(B1, 0, 1); PG8_SCHED; PG8_LDA(At, 0, 0); PG8_STAGE(PG8_SA(1, 1), a1 + hstepA, voffA);
;             PG8_WAIT_V(8); PG8_WAIT_L(0); PG8_BAR; PG8_MMA(0, 0, At, B0); PG8_MMA(0, 1, At, B1); PG8_BAR; PG8_SCHED;
;             PG8_LDA(At, 0, 1); PG8_STAGE(PG8_SB(0, 0), b2, voffB); PG8_STAGE(PG8_SB(0, 1), b2 + hstep, voffB); PG8_STAGE(PG8_SA(0, 0), a2, voffA);
;             PG8_WAIT_V(8); PG8_WAIT_L(0); PG8_BAR; PG8_MMA(1, 0, At, B0); PG8_MMA(1, 1, At, B1); PG8_BAR; PG8_SCHED;
	v_mfma_f32_16x16x32_bf16 v[122:125], v[140:143], v[174:177], v[122:125]
	v_mfma_f32_16x16x32_bf16 v[114:117], v[150:153], v[174:177], v[114:117]
	v_mfma_f32_16x16x32_bf16 v[106:109], v[140:143], v[198:201], v[106:109]
	v_mfma_f32_16x16x32_bf16 v[98:101], v[150:153], v[198:201], v[98:101]
	v_mfma_f32_16x16x32_bf16 v[90:93], v[140:143], v[206:209], v[90:93]
	v_mfma_f32_16x16x32_bf16 v[82:85], v[150:153], v[206:209], v[82:85]
	v_mfma_f32_16x16x32_bf16 v[74:77], v[140:143], v[214:217], v[74:77]
	v_mfma_f32_16x16x32_bf16 v[66:69], v[150:153], v[214:217], v[66:69]
	v_mfma_f32_16x16x32_bf16 v[122:125], v[144:147], v[194:197], v[122:125]
	v_mfma_f32_16x16x32_bf16 v[114:117], v[154:157], v[194:197], v[114:117]
	v_mfma_f32_16x16x32_bf16 v[106:109], v[144:147], v[202:205], v[106:109]
	v_mfma_f32_16x16x32_bf16 v[98:101], v[154:157], v[202:205], v[98:101]
	v_mfma_f32_16x16x32_bf16 v[90:93], v[144:147], v[210:213], v[90:93]
	v_mfma_f32_16x16x32_bf16 v[82:85], v[154:157], v[210:213], v[82:85]
	v_mfma_f32_16x16x32_bf16 v[74:77], v[144:147], v[218:221], v[74:77]
	v_mfma_f32_16x16x32_bf16 v[66:69], v[154:157], v[218:221], v[66:69]
	v_mfma_f32_16x16x32_bf16 v[126:129], v[158:161], v[174:177], v[126:129]
	v_mfma_f32_16x16x32_bf16 v[118:121], v[166:169], v[174:177], v[118:121]
	v_mfma_f32_16x16x32_bf16 v[110:113], v[158:161], v[198:201], v[110:113]
	v_mfma_f32_16x16x32_bf16 v[102:105], v[166:169], v[198:201], v[102:105]
	v_mfma_f32_16x16x32_bf16 v[94:97], v[158:161], v[206:209], v[94:97]
	v_mfma_f32_16x16x32_bf16 v[86:89], v[166:169], v[206:209], v[86:89]
	v_mfma_f32_16x16x32_bf16 v[78:81], v[158:161], v[214:217], v[78:81]
	v_mfma_f32_16x16x32_bf16 v[70:73], v[166:169], v[214:217], v[70:73]
	v_mfma_f32_16x16x32_bf16 v[126:129], v[162:165], v[194:197], v[126:129]
	v_mfma_f32_16x16x32_bf16 v[118:121], v[170:173], v[194:197], v[118:121]
	v_mfma_f32_16x16x32_bf16 v[110:113], v[162:165], v[202:205], v[110:113]
	v_mfma_f32_16x16x32_bf16 v[102:105], v[170:173], v[202:205], v[102:105]
	v_mfma_f32_16x16x32_bf16 v[94:97], v[162:165], v[210:213], v[94:97]
	v_mfma_f32_16x16x32_bf16 v[86:89], v[170:173], v[210:213], v[86:89]
	v_mfma_f32_16x16x32_bf16 v[78:81], v[162:165], v[218:221], v[78:81]
	v_mfma_f32_16x16x32_bf16 v[70:73], v[170:173], v[218:221], v[70:73]
	s_barrier
	s_add_i32 s84, s84, s31
	v_lshl_add_u64 v[178:179], s[46:47], 0, v[134:135]
	s_mov_b32 m0, s84
	ds_read_b128 v[174:177], v149 offset:16384
	ds_read_b128 v[194:197], v149 offset:17408
	ds_read_b128 v[198:201], v149 offset:18432
	ds_read_b128 v[202:205], v149 offset:19456
	ds_read_b128 v[206:209], v149 offset:20480
	ds_read_b128 v[210:213], v149 offset:21504
	ds_read_b128 v[214:217], v149 offset:22528
	ds_read_b128 v[218:221], v149 offset:23552
	global_load_lds_dwordx4 v[178:179], off
	s_add_i32 m0, s84, 0x2000
	s_add_u32 s84, s46, 0x40000
	v_lshl_add_u64 v[180:181], s[46:47], 0, v[130:131]
	s_addc_u32 s85, s47, 0
	s_add_i32 s86, s86, s31
	global_load_lds_dwordx4 v[180:181], off
	v_lshl_add_u64 v[182:183], s[84:85], 0, v[134:135]
	s_mov_b32 m0, s86
	v_lshl_add_u64 v[188:189], s[54:55], 0, v[132:133]
	global_load_lds_dwordx4 v[182:183], off
	v_lshl_add_u64 v[182:183], s[84:85], 0, v[130:131]
	s_add_i32 m0, s86, 0x2000
	s_nop 0
	global_load_lds_dwordx4 v[182:183], off
	v_lshl_add_u64 v[182:183], s[54:55], 0, v[136:137]
	s_mov_b32 m0, s38
	s_nop 0
	global_load_lds_dwordx4 v[182:183], off
	s_mov_b32 m0, s48
	s_nop 0
	global_load_lds_dwordx4 v[188:189], off
	s_waitcnt vmcnt(8)
	s_waitcnt lgkmcnt(0)
	s_barrier
	v_mfma_f32_16x16x32_bf16 v[58:61], v[140:143], v[174:177], v[58:61]
	v_mfma_f32_16x16x32_bf16 v[50:53], v[150:153], v[174:177], v[50:53]
	v_mfma_f32_16x16x32_bf16 v[42:45], v[140:143], v[198:201], v[42:45]
	v_mfma_f32_16x16x32_bf16 v[34:37], v[150:153], v[198:201], v[34:37]
	v_mfma_f32_16x16x32_bf16 v[26:29], v[140:143], v[206:209], v[26:29]
	v_mfma_f32_16x16x32_bf16 v[18:21], v[150:153], v[206:209], v[18:21]
	v_mfma_f32_16x16x32_bf16 v[10:13], v[140:143], v[214:217], v[10:13]
	v_mfma_f32_16x16x32_bf16 v[6:9], v[150:153], v[214:217], v[6:9]
	v_mfma_f32_16x16x32_bf16 v[58:61], v[144:147], v[194:197], v[58:61]
	v_mfma_f32_16x16x32_bf16 v[50:53], v[154:157], v[194:197], v[50:53]
	v_mfma_f32_16x16x32_bf16 v[42:45], v[144:147], v[202:205], v[42:45]
	v_mfma_f32_16x16x32_bf16 v[34:37], v[154:157], v[202:205], v[34:37]
	v_mfma_f32_16x16x32_bf16 v[26:29], v[144:147], v[210:213], v[26:29]
	v_mfma_f32_16x16x32_bf16 v[18:21], v[154:157], v[210:213], v[18:21]
	v_mfma_f32_16x16x32_bf16 v[10:13], v[144:147], v[218:221], v[10:13]
	v_mfma_f32_16x16x32_bf16 v[6:9], v[154:157], v[218:221], v[6:9]
	v_mfma_f32_16x16x32_bf16 v[62:65], v[158:161], v[174:177], v[62:65]
	v_mfma_f32_16x16x32_bf16 v[54:57], v[166:169], v[174:177], v[54:57]
	v_mfma_f32_16x16x32_bf16 v[46:49], v[158:161], v[198:201], v[46:49]
	v_mfma_f32_16x16x32_bf16 v[38:41], v[166:169], v[198:201], v[38:41]
	v_mfma_f32_16x16x32_bf16 v[30:33], v[158:161], v[206:209], v[30:33]
	v_mfma_f32_16x16x32_bf16 v[22:25], v[166:169], v[206:209], v[22:25]
	v_mfma_f32_16x16x32_bf16 v[14:17], v[158:161], v[214:217], v[14:17]
	v_mfma_f32_16x16x32_bf16 v[2:5], v[166:169], v[214:217], v[2:5]
	v_mfma_f32_16x16x32_bf16 v[62:65], v[162:165], v[194:197], v[62:65]
	v_mfma_f32_16x16x32_bf16 v[54:57], v[170:173], v[194:197], v[54:57]
	v_mfma_f32_16x16x32_bf16 v[46:49], v[162:165], v[202:205], v[46:49]
	v_mfma_f32_16x16x32_bf16 v[38:41], v[170:173], v[202:205], v[38:41]
	v_mfma_f32_16x16x32_bf16 v[30:33], v[162:165], v[210:213], v[30:33]
	v_mfma_f32_16x16x32_bf16 v[22:25], v[170:173], v[210:213], v[22:25]
	v_mfma_f32_16x16x32_bf16 v[14:17], v[162:165], v[218:221], v[14:17]
	v_mfma_f32_16x16x32_bf16 v[2:5], v[170:173], v[218:221], v[2:5]
	s_barrier
; #define PG8_STAGE(bufoff, gbase, voff) do { _Pragma("unroll") for (int _i = 0; _i < 2; ++_i) \
;         __builtin_amdgcn_global_load_lds((const unsigned*)((const char*)(gbase) + (voff)[_i]), (LAS unsigned*)(lds + (bufoff) + ldsw + _i * 8192), 16, 0, 0); } while (0)
; #define PG8_LDA(dst, b, h) do { _Pragma("unroll") for (int m = 0; m < 4; ++m) _Pragma("unroll") for (int k = 0; k < 2; ++k) dst[m][k] = *(const LAS bf16x8*)(lds + PG8_SA(b, h) + aoff + m * 2048 + k * 1024); } while (0)
; #define PG8_LDB(dst, b, h) do { _Pragma("unroll") for (int n = 0; n < 2; ++n) _Pragma("unroll") for (int k = 0; k < 2; ++k) dst[n][k] = *(const LAS bf16x8*)(lds + PG8_SB(b, h) + boff + n * 2048 + k * 1024); } while (0)
; #define PG8_MMA(ai, bj, At, Bt) do { __builtin_amdgcn_s_setprio(1); _Pragma("unroll") for (int m = 0; m < 4; ++m) _Pragma("unroll") for (int n = 0; n < 2; ++n) _Pragma("unroll") for (int k = 0; k < 2; ++k) \
;         acc[ai][bj][m][n] = __builtin_amdgcn_mfma_f32_16x16x32_bf16(Bt[n][k], At[m][k], acc[ai][bj][m][n], 0, 0, 0); __builtin_amdgcn_s_setprio(0); } while (0)
; #define PG8_WAIT_V(n) asm volatile("s_waitcnt vmcnt(" #n ")" ::: "memory")
; #define PG8_WAIT_L(n) asm volatile("s_waitcnt lgkmcnt(" #n ")" ::: "memory")
; #define PG8_BAR __builtin_amdgcn_s_barrier()
; #define PG8_SCHED __builtin_amdgcn_sched_barrier(0)
; template <class Epi, class Pre, bool AG = false>
; __device__ __forceinline__ void gemm_phase(LAS unsigned char* lds, const Gemm g, const StaticOrder& S, const Epi& E, const Pre& P) {
;     ...
;             PG8_LDB(B0, 1, 0); PG8_LDB(B1, 1, 1); PG8_SCHED; PG8_LDA(At, 1, 0); PG8_STAGE(PG8_SA(0, 1), a2 + hstepA, voffA);
;             PG8_WAIT_V(8); PG8_WAIT_L(0); PG8_BAR; PG8_MMA(0, 0, At, B0); PG8_MMA(0, 1, At, B1); PG8_BAR; PG8_SCHED;
;             PG8_LDA(At, 1, 1); PG8_STAGE(PG8_SB(1, 0), b3, voffB); PG8_STAGE(PG8_SB(1, 1), b3 + hstep, voffB); PG8_STAGE(PG8_SA(1, 0), a3, voffA);
;             PG8_WAIT_V(8); PG8_WAIT_L(0); PG8_BAR; PG8_MMA(1, 0, At, B0); PG8_MMA(1, 1, At, B1); PG8_BAR; PG8_SCHED;
	s_add_i32 s84, 0, 0x18000
	s_add_i32 s85, 0, 0x1c000
	v_add_u32_e32 v154, s84, v148
	v_add_u32_e32 v170, s85, v148
	ds_read_b128 v[140:143], v154
	ds_read_b128 v[144:147], v154 offset:1024
	ds_read_b128 v[150:153], v154 offset:2048
	ds_read_b128 v[154:157], v154 offset:3072
	ds_read_b128 v[158:161], v170
	ds_read_b128 v[162:165], v170 offset:1024
	ds_read_b128 v[166:169], v170 offset:2048
	ds_read_b128 v[170:173], v170 offset:3072
	s_add_u32 s54, s54, 0x40000
	s_addc_u32 s55, s55, 0
	s_mov_b32 m0, s49
	v_lshl_add_u64 v[190:191], s[54:55], 0, v[136:137]
	ds_read_b128 v[174:177], v149 offset:32768
	ds_read_b128 v[194:197], v149 offset:33792
	ds_read_b128 v[198:201], v149 offset:34816
	ds_read_b128 v[202:205], v149 offset:35840
	ds_read_b128 v[206:209], v149 offset:36864
	ds_read_b128 v[210:213], v149 offset:37888
	ds_read_b128 v[214:217], v149 offset:38912
	ds_read_b128 v[218:221], v149 offset:39936
	global_load_lds_dwordx4 v[190:191], off
	v_lshl_add_u64 v[190:191], s[54:55], 0, v[132:133]
	s_mov_b32 m0, s53
	s_nop 0
	global_load_lds_dwordx4 v[190:191], off
	s_waitcnt vmcnt(8)
	s_waitcnt lgkmcnt(0)
	s_barrier
	v_mfma_f32_16x16x32_bf16 v[122:125], v[140:143], v[174:177], v[122:125]
	v_mfma_f32_16x16x32_bf16 v[114:117], v[150:153], v[174:177], v[114:117]
	v_mfma_f32_16x16x32_bf16 v[106:109], v[140:143], v[198:201], v[106:109]
	v_mfma_f32_16x16x32_bf16 v[98:101], v[150:153], v[198:201], v[98:101]
	v_mfma_f32_16x16x32_bf16 v[90:93], v[140:143], v[206:209], v[90:93]
	v_mfma_f32_16x16x32_bf16 v[82:85], v[150:153], v[206:209], v[82:85]
	v_mfma_f32_16x16x32_bf16 v[74:77], v[140:143], v[214:217], v[74:77]
	v_mfma_f32_16x16x32_bf16 v[66:69], v[150:153], v[214:217], v[66:69]
	v_mfma_f32_16x16x32_bf16 v[122:125], v[144:147], v[194:197], v[122:125]
	v_mfma_f32_16x16x32_bf16 v[114:117], v[154:157], v[194:197], v[114:117]
	v_mfma_f32_16x16x32_bf16 v[106:109], v[144:147], v[202:205], v[106:109]
	v_mfma_f32_16x16x32_bf16 v[98:101], v[154:157], v[202:205], v[98:101]
	v_mfma_f32_16x16x32_bf16 v[90:93], v[144:147], v[210:213], v[90:93]
	v_mfma_f32_16x16x32_bf16 v[82:85], v[154:157], v[210:213], v[82:85]
	v_mfma_f32_16x16x32_bf16 v[74:77], v[144:147], v[218:221], v[74:77]
	v_mfma_f32_16x16x32_bf16 v[66:69], v[154:157], v[218:221], v[66:69]
	v_mfma_f32_16x16x32_bf16 v[126:129], v[158:161], v[174:177], v[126:129]
	v_mfma_f32_16x16x32_bf16 v[118:121], v[166:169], v[174:177], v[118:121]
	v_mfma_f32_16x16x32_bf16 v[110:113], v[158:161], v[198:201], v[110:113]
	v_mfma_f32_16x16x32_bf16 v[102:105], v[166:169], v[198:201], v[102:105]
	v_mfma_f32_16x16x32_bf16 v[94:97], v[158:161], v[206:209], v[94:97]
	v_mfma_f32_16x16x32_bf16 v[86:89], v[166:169], v[206:209], v[86:89]
	v_mfma_f32_16x16x32_bf16 v[78:81], v[158:161], v[214:217], v[78:81]
	v_mfma_f32_16x16x32_bf16 v[70:73], v[166:169], v[214:217], v[70:73]
	v_mfma_f32_16x16x32_bf16 v[126:129], v[162:165], v[194:197], v[126:129]
	v_mfma_f32_16x16x32_bf16 v[118:121], v[170:173], v[194:197], v[118:121]
	v_mfma_f32_16x16x32_bf16 v[110:113], v[162:165], v[202:205], v[110:113]
	v_mfma_f32_16x16x32_bf16 v[102:105], v[170:173], v[202:205], v[102:105]
	v_mfma_f32_16x16x32_bf16 v[94:97], v[162:165], v[210:213], v[94:97]
	v_mfma_f32_16x16x32_bf16 v[86:89], v[170:173], v[210:213], v[86:89]
	v_mfma_f32_16x16x32_bf16 v[78:81], v[162:165], v[218:221], v[78:81]
	v_mfma_f32_16x16x32_bf16 v[70:73], v[170:173], v[218:221], v[70:73]
	s_barrier
	s_add_i32 s54, s84, s31
	v_lshl_add_u64 v[178:179], v[178:179], 0, s[66:67]
	s_mov_b32 m0, s54
	ds_read_b128 v[174:177], v149 offset:49152
	ds_read_b128 v[194:197], v149 offset:50176
	ds_read_b128 v[198:201], v149 offset:51200
	ds_read_b128 v[202:205], v149 offset:52224
	ds_read_b128 v[206:209], v149 offset:53248
	ds_read_b128 v[210:213], v149 offset:54272
	ds_read_b128 v[214:217], v149 offset:55296
	ds_read_b128 v[218:221], v149 offset:56320
	global_load_lds_dwordx4 v[178:179], off
	s_add_i32 m0, s54, 0x2000
	s_add_u32 s46, s46, 0x40080
	v_lshl_add_u64 v[178:179], v[180:181], 0, s[66:67]
	s_addc_u32 s47, s47, 0
	s_add_i32 s54, s85, s31
	global_load_lds_dwordx4 v[178:179], off
	v_lshl_add_u64 v[178:179], s[46:47], 0, v[134:135]
	s_mov_b32 m0, s54
	s_nop 0
	global_load_lds_dwordx4 v[178:179], off
	v_lshl_add_u64 v[178:179], s[46:47], 0, v[130:131]
	s_add_i32 m0, s54, 0x2000
	s_nop 0
	global_load_lds_dwordx4 v[178:179], off
	v_lshl_add_u64 v[178:179], v[182:183], 0, s[66:67]
	s_mov_b32 m0, s58
	s_nop 0
	global_load_lds_dwordx4 v[178:179], off
	v_lshl_add_u64 v[178:179], v[188:189], 0, s[66:67]
	s_mov_b32 m0, s59
	s_nop 0
	global_load_lds_dwordx4 v[178:179], off
	s_waitcnt vmcnt(8)
	s_waitcnt lgkmcnt(0)
	s_barrier
	v_mfma_f32_16x16x32_bf16 v[58:61], v[140:143], v[174:177], v[58:61]
	v_mfma_f32_16x16x32_bf16 v[50:53], v[150:153], v[174:177], v[50:53]
	v_mfma_f32_16x16x32_bf16 v[42:45], v[140:143], v[198:201], v[42:45]
	v_mfma_f32_16x16x32_bf16 v[34:37], v[150:153], v[198:201], v[34:37]
	v_mfma_f32_16x16x32_bf16 v[26:29], v[140:143], v[206:209], v[26:29]
	v_mfma_f32_16x16x32_bf16 v[18:21], v[150:153], v[206:209], v[18:21]
	v_mfma_f32_16x16x32_bf16 v[10:13], v[140:143], v[214:217], v[10:13]
	v_mfma_f32_16x16x32_bf16 v[6:9], v[150:153], v[214:217], v[6:9]
	v_mfma_f32_16x16x32_bf16 v[58:61], v[144:147], v[194:197], v[58:61]
	v_mfma_f32_16x16x32_bf16 v[50:53], v[154:157], v[194:197], v[50:53]
	v_mfma_f32_16x16x32_bf16 v[42:45], v[144:147], v[202:205], v[42:45]
	v_mfma_f32_16x16x32_bf16 v[34:37], v[154:157], v[202:205], v[34:37]
	v_mfma_f32_16x16x32_bf16 v[26:29], v[144:147], v[210:213], v[26:29]
	v_mfma_f32_16x16x32_bf16 v[18:21], v[154:157], v[210:213], v[18:21]
	v_mfma_f32_16x16x32_bf16 v[10:13], v[144:147], v[218:221], v[10:13]
	v_mfma_f32_16x16x32_bf16 v[6:9], v[154:157], v[218:221], v[6:9]
	v_mfma_f32_16x16x32_bf16 v[62:65], v[158:161], v[174:177], v[62:65]
	v_mfma_f32_16x16x32_bf16 v[54:57], v[166:169], v[174:177], v[54:57]
	v_mfma_f32_16x16x32_bf16 v[46:49], v[158:161], v[198:201], v[46:49]
	v_mfma_f32_16x16x32_bf16 v[38:41], v[166:169], v[198:201], v[38:41]
	v_mfma_f32_16x16x32_bf16 v[30:33], v[158:161], v[206:209], v[30:33]
	v_mfma_f32_16x16x32_bf16 v[22:25], v[166:169], v[206:209], v[22:25]
	v_mfma_f32_16x16x32_bf16 v[14:17], v[158:161], v[214:217], v[14:17]
	v_mfma_f32_16x16x32_bf16 v[2:5], v[166:169], v[214:217], v[2:5]
	v_mfma_f32_16x16x32_bf16 v[62:65], v[162:165], v[194:197], v[62:65]
	v_mfma_f32_16x16x32_bf16 v[54:57], v[170:173], v[194:197], v[54:57]
	v_mfma_f32_16x16x32_bf16 v[46:49], v[162:165], v[202:205], v[46:49]
	v_mfma_f32_16x16x32_bf16 v[38:41], v[170:173], v[202:205], v[38:41]
	v_mfma_f32_16x16x32_bf16 v[30:33], v[162:165], v[210:213], v[30:33]
	v_mfma_f32_16x16x32_bf16 v[22:25], v[170:173], v[210:213], v[22:25]
	v_mfma_f32_16x16x32_bf16 v[14:17], v[162:165], v[218:221], v[14:17]
	v_mfma_f32_16x16x32_bf16 v[2:5], v[170:173], v[218:221], v[2:5]
	s_barrier
	s_add_i32 s79, s79, 2
	s_add_u32 s44, s44, 0x100
	s_addc_u32 s45, s45, 0
	s_add_u32 s76, s76, 0x100
	s_addc_u32 s77, s77, 0
	s_cmp_gt_u32 s79, 13
	s_cbranch_scc0 .LBB0_212

; #define PG8_WAIT_V(n) asm volatile("s_waitcnt vmcnt(" #n ")" ::: "memory")
; #define PG8_BAR __builtin_amdgcn_s_barrier()
; template <class Epi, class Pre, bool AG = false>
; __device__ __forceinline__ void gemm_phase(LAS unsigned char* lds, const Gemm g, const StaticOrder& S, const Epi& E, const Pre& P) {
;     ...
;     PG8_WAIT_V(0);
;     PG8_BAR;
.LBB0_218:
	s_setprio 0
	s_waitcnt vmcnt(0)
	s_movk_i32 s38, 0x5000
	s_mov_b32 s53, 0x1b000
	s_barrier
